# resid gemm80 loop: 3-stage ring with a single barrier per iteration (tile k+2 issued after the fragment reads of tile k)
# speedup vs baseline: 1.0008x; 1.0008x over previous
.Lr80_wd:
	s_waitcnt lgkmcnt(0)
	s_barrier
	v_add_u32_e32 v60, s41, v58
	v_add_u32_e32 v59, s41, v43
	v_add_u32_e32 v116, s41, v56
	v_add_u32_e32 v117, v60, v43
	v_add_u32_e32 v118, v60, v56
	ds_read_b128 v[60:63], v59
	ds_read_b128 v[64:67], v59 offset:2048
	ds_read_b128 v[68:71], v59 offset:4096
	ds_read_b128 v[72:75], v59 offset:6144
	ds_read_b128 v[76:79], v59 offset:8192
	ds_read_b128 v[80:83], v117
	ds_read_b128 v[84:87], v117 offset:2048
	ds_read_b128 v[88:91], v116
	ds_read_b128 v[92:95], v116 offset:2048
	ds_read_b128 v[96:99], v116 offset:4096
	ds_read_b128 v[100:103], v116 offset:6144
	ds_read_b128 v[104:107], v116 offset:8192
	ds_read_b128 v[108:111], v118
	ds_read_b128 v[112:115], v118 offset:2048
	s_add_i32 s58, s26, 2
	s_cmp_lt_u32 s58, s65
	s_cbranch_scc0 .Lr80_nd
	s_add_i32 s71, s41, 0xd000
	s_cmp_lt_u32 s71, 0x13800
	s_cbranch_scc1 .Lr80_st
	s_sub_u32 s71, s71, 0x13800
.Lr80_st:
	v_add_u32_e32 v134, s71, v42
	s_lshl_b64 s[56:57], s[28:29], 1
	v_readfirstlane_b32 s58, v134
	v_add_u32_e32 v135, 0x1000, v134
	v_lshl_add_u64 v[136:137], v[40:41], 0, s[56:57]
	s_mov_b32 m0, s58
	v_readfirstlane_b32 s58, v135
	global_load_lds_dwordx4 v[136:137], off
	v_lshl_add_u64 v[136:137], v[44:45], 0, s[56:57]
	s_mov_b32 m0, s58
	s_nop 0
	global_load_lds_dwordx4 v[136:137], off
	s_and_saveexec_b64 s[58:59], s[38:39]
	s_cbranch_execz .Lr80i_noA3
	v_add_u32_e32 v134, 0x2000, v134
	v_lshl_add_u64 v[136:137], s[28:29], 1, v[46:47]
	v_readfirstlane_b32 s72, v134
	s_mov_b32 m0, s72
	s_nop 0
	global_load_lds_dwordx4 v[136:137], off
.Lr80i_noA3:
	s_or_b64 exec, exec, s[58:59]
	v_add_u32_e32 v134, s71, v57
	v_add_u32_e32 v135, 0x2800, v134
	v_lshl_add_u64 v[136:137], v[48:49], 0, s[56:57]
	v_readfirstlane_b32 s58, v135
	v_add_u32_e32 v135, 0x2c00, v134
	s_mov_b32 m0, s58
	v_readfirstlane_b32 s58, v135
	v_add_u32_e32 v135, 0x3000, v134
	global_load_lds_dwordx4 v[136:137], off
	v_lshl_add_u64 v[136:137], v[50:51], 0, s[56:57]
	s_mov_b32 m0, s58
	v_readfirstlane_b32 s58, v135
	global_load_lds_dwordx4 v[136:137], off
	v_lshl_add_u64 v[136:137], v[52:53], 0, s[56:57]
	s_mov_b32 m0, s58
	v_add_u32_e32 v134, 0x3400, v134
	global_load_lds_dwordx4 v[136:137], off
	v_lshl_add_u64 v[136:137], v[54:55], 0, s[56:57]
	v_readfirstlane_b32 s56, v134
	s_mov_b32 m0, s56
	s_nop 0
	global_load_lds_dwordx4 v[136:137], off
.Lr80_nd:
	s_waitcnt lgkmcnt(7)
	v_mfma_f32_16x16x32_bf16 v[36:39], v[80:83], v[60:63], v[36:39]
	v_mfma_f32_16x16x32_bf16 v[32:35], v[84:87], v[60:63], v[32:35]
	v_mfma_f32_16x16x32_bf16 v[28:31], v[80:83], v[64:67], v[28:31]
	v_mfma_f32_16x16x32_bf16 v[24:27], v[84:87], v[64:67], v[24:27]
	v_mfma_f32_16x16x32_bf16 v[20:23], v[80:83], v[68:71], v[20:23]
	v_mfma_f32_16x16x32_bf16 v[16:19], v[84:87], v[68:71], v[16:19]
	v_mfma_f32_16x16x32_bf16 v[12:15], v[80:83], v[72:75], v[12:15]
	v_mfma_f32_16x16x32_bf16 v[0:3], v[80:83], v[76:79], v[0:3]
	v_mfma_f32_16x16x32_bf16 v[4:7], v[84:87], v[76:79], v[4:7]
	v_mfma_f32_16x16x32_bf16 v[8:11], v[84:87], v[72:75], v[8:11]
	s_waitcnt lgkmcnt(0)
	s_nop 0
	v_mfma_f32_16x16x32_bf16 v[36:39], v[108:111], v[88:91], v[36:39]
	v_mfma_f32_16x16x32_bf16 v[32:35], v[112:115], v[88:91], v[32:35]
	v_mfma_f32_16x16x32_bf16 v[28:31], v[108:111], v[92:95], v[28:31]
	v_mfma_f32_16x16x32_bf16 v[24:27], v[112:115], v[92:95], v[24:27]
	v_mfma_f32_16x16x32_bf16 v[20:23], v[108:111], v[96:99], v[20:23]
	v_mfma_f32_16x16x32_bf16 v[16:19], v[112:115], v[96:99], v[16:19]
	v_mfma_f32_16x16x32_bf16 v[12:15], v[108:111], v[100:103], v[12:15]
	v_mfma_f32_16x16x32_bf16 v[8:11], v[112:115], v[100:103], v[8:11]
	v_mfma_f32_16x16x32_bf16 v[0:3], v[108:111], v[104:107], v[0:3]
	v_mfma_f32_16x16x32_bf16 v[4:7], v[112:115], v[104:107], v[4:7]
	s_add_i32 s26, s26, 1
	s_add_i32 s28, s28, 64
	s_add_i32 s41, s41, 0x6800
	s_cmp_eq_u32 s41, 0x13800
	s_cselect_b32 s41, 0, s41
	s_cmp_lg_u32 s26, s65
	s_cbranch_scc1 .LBB0_266
